# v26 + age-favoured wave half issues H1 staging loads before the barrier (they wait there anyway); bit-identical
# speedup vs baseline: 1.0036x; 1.0036x over previous
; template <int KB, bool HASY>
; __device__ __forceinline__ void phaseA(f32x16& X0, f32x16& X1, f32x16& Y0, f32x16& Y1, bf16x8& pa0, bf16x8& pa1, bf16x8& pa2, bf16x8& pa3,
;                                        const bf16x8* qr, const f32x16& negm, int kaddr, VFr& vf, int vb, float& l_reg) {
;   SBAR();
;   float ls = 0.f;
;   bf16x8 k0 = rd128<KOFF(KB, 0, 0)>(kaddr), k1 = rd128<KOFF(KB, 1, 0)>(kaddr), k2 = rd128<KOFF(KB, 0, 1)>(kaddr), k3 = rd128<KOFF(KB, 1, 1)>(kaddr);
;   if (HASY) { EXP4(Y0, 0); EXP4(Y0, 4); }
;   SBAR(); WAIT4(k0, k1, k2, k3);
;   bf16x8 k4 = rd128<KOFF(KB, 0, 2)>(kaddr), k5 = rd128<KOFF(KB, 1, 2)>(kaddr), k6 = rd128<KOFF(KB, 0, 3)>(kaddr), k7 = rd128<KOFF(KB, 1, 3)>(kaddr);
;   SBAR();
;   X0 = MF(k0, qr[0], negm); if (HASY) { EXP4(Y0, 8); SUM4(Y0, 0); } SBAR();
;   X1 = MF(k1, qr[0], negm); if (HASY) { EXP4(Y0, 12); SUM4(Y0, 4); } SBAR();
;   X0 = MF(k2, qr[1], X0); if (HASY) { PACK8(Y0, 0, pa0); } SBAR();
;   X1 = MF(k3, qr[1], X1); if (HASY) { EXP4(Y1, 0); SUM4(Y0, 8); } SBAR();
;   WAIT4(k4, k5, k6, k7);
;   bf16x8 k8 = rd128<KOFF(KB, 0, 4)>(kaddr), k9 = rd128<KOFF(KB, 1, 4)>(kaddr), k10 = rd128<KOFF(KB, 0, 5)>(kaddr), k11 = rd128<KOFF(KB, 1, 5)>(kaddr);
;   SBAR();
;   X0 = MF(k4, qr[2], X0); if (HASY) { EXP4(Y1, 4); SUM4(Y0, 12); } SBAR();
;   X1 = MF(k5, qr[2], X1); if (HASY) { PACK8(Y0, 8, pa1); } SBAR();
;   X0 = MF(k6, qr[3], X0); if (HASY) { EXP4(Y1, 8); SUM4(Y1, 0); } SBAR();
;   X1 = MF(k7, qr[3], X1); if (HASY) { EXP4(Y1, 12); SUM4(Y1, 4); } SBAR();
;   WAIT4(k8, k9, k10, k11);
;   SBAR();
;   X0 = MF(k8, qr[4], X0); if (HASY) { PACK8(Y1, 0, pa2); } SBAR();
;   X1 = MF(k9, qr[4], X1); if (HASY) { SUM4(Y1, 8); SUM4(Y1, 12); } SBAR();
;   X0 = MF(k10, qr[5], X0); if (HASY) { PACK8(Y1, 8, pa3); } SBAR();
;   X1 = MF(k11, qr[5], X1); if (HASY) vfr_issue<0>(vf, vb);
;   l_reg += ls;
;   SBAR();
; }
; template <bool HASX>
; __device__ __forceinline__ float phaseB(f32x16* o, bf16x8 pa0, bf16x8 pa1, bf16x8 pa2, bf16x8 pa3, VFr& f, int vb, const f32x16& X0, const f32x16& X1) {
;   SBAR(); VWAIT(f); VFr g; vfr_issue<2>(g, vb); SBAR();
;   float a = 0.f, b = 0.f;
;   o[0] = MF(pa0, PKV(f.a0, f.b0), o[0]); SBAR(); o[1] = MF(pa0, PKV(f.c0, f.d0), o[1]);
;   if (HASX) { a = MX3(X0[0], X0[1], X1[0]); b = MX3(X0[2], X0[3], X1[1]); a = MX3(a, X1[2], X1[3]); b = MX3(b, X0[4], X0[5]); } SBAR();
.LBB0_259:
	v_add_u32_e32 v237, s76, v192
	s_cmp_ge_u32 s39, s38
	s_cselect_b64 s[18:19], -1, 0
	s_and_b64 vcc, exec, s[18:19]
	s_cbranch_vccnz .LBB0_263
	buffer_load_dwordx4 v[162:165], v185, s[64:67], s52 offen
	buffer_load_dwordx4 v[166:169], v185, s[44:47], s52 offen
	buffer_load_dwordx4 v[154:157], v186, s[60:63], s68 offen
.LBB0_263:
	v_exp_f32_e32 v195, v114
	v_exp_f32_e32 v197, v115
	v_exp_f32_e32 v198, v116
	v_exp_f32_e32 v201, v117
	v_exp_f32_e32 v196, v118
	v_exp_f32_e32 v199, v119
	v_exp_f32_e32 v200, v120
	v_exp_f32_e32 v202, v121
	s_waitcnt lgkmcnt(0)
	s_barrier
	ds_read_b128 v[66:69], v184 offset:0
	ds_read_b128 v[212:215], v184 offset:0x1a00
	ds_read_b128 v[216:219], v184 offset:32
	ds_read_b128 v[118:121], v184 offset:0x1a20
	ds_read_b128 v[220:223], v184 offset:64
	ds_read_b128 v[228:231], v184 offset:0x1a40
	ds_read_b128 v[238:241], v184 offset:0x60
	ds_read_b128 v[242:245], v184 offset:0x1a60
	s_waitcnt lgkmcnt(7)
	v_mfma_f32_32x32x16_bf16 v[82:97], v[66:69], v[150:153], v[50:65]
	v_exp_f32_e32 v203, v122
	v_exp_f32_e32 v204, v123
	v_exp_f32_e32 v205, v124
	v_exp_f32_e32 v206, v125
	s_waitcnt lgkmcnt(6)
	v_mfma_f32_32x32x16_bf16 v[66:81], v[212:215], v[150:153], v[50:65]
	v_exp_f32_e32 v207, v126
	v_exp_f32_e32 v208, v127
	v_exp_f32_e32 v209, v128
	v_exp_f32_e32 v210, v129
	s_waitcnt lgkmcnt(5)
	v_mfma_f32_32x32x16_bf16 v[82:97], v[216:219], v[146:149], v[82:97]
	v_cvt_pk_bf16_f32 v114, v195, v197
	v_cvt_pk_bf16_f32 v115, v198, v201
	v_cvt_pk_bf16_f32 v116, v196, v199
	v_cvt_pk_bf16_f32 v117, v200, v202
	s_waitcnt lgkmcnt(4)
	v_mfma_f32_32x32x16_bf16 v[66:81], v[118:121], v[146:149], v[66:81]
	v_exp_f32_e32 v211, v98
	v_exp_f32_e32 v212, v99
	v_exp_f32_e32 v213, v100
	v_exp_f32_e32 v214, v101
	ds_read_b128 v[98:101], v184 offset:0x80
	ds_read_b128 v[118:121], v184 offset:0x1a80
	ds_read_b128 v[122:125], v184 offset:0xa0
	ds_read_b128 v[246:249], v184 offset:0x1aa0
	s_waitcnt lgkmcnt(4)
	v_mfma_f32_32x32x16_bf16 v[82:97], v[220:223], v[142:145], v[82:97]
	v_exp_f32_e32 v215, v102
	v_exp_f32_e32 v216, v103
	v_exp_f32_e32 v217, v104
	v_exp_f32_e32 v218, v105
	v_mfma_f32_32x32x16_bf16 v[66:81], v[228:231], v[142:145], v[66:81]
	v_cvt_pk_bf16_f32 v102, v203, v204
	v_cvt_pk_bf16_f32 v103, v205, v206
	v_cvt_pk_bf16_f32 v104, v207, v208
	v_cvt_pk_bf16_f32 v105, v209, v210
	v_mfma_f32_32x32x16_bf16 v[82:97], v[238:241], v[138:141], v[82:97]
	v_exp_f32_e32 v219, v106
	v_exp_f32_e32 v220, v107
	v_exp_f32_e32 v221, v108
	v_exp_f32_e32 v222, v109
	v_mfma_f32_32x32x16_bf16 v[66:81], v[242:245], v[138:141], v[66:81]
	v_exp_f32_e32 v223, v110
	v_exp_f32_e32 v234, v111
	v_exp_f32_e32 v235, v112
	v_exp_f32_e32 v236, v113
	s_waitcnt lgkmcnt(0)
	s_nop 0
	v_mfma_f32_32x32x16_bf16 v[82:97], v[98:101], v[134:137], v[82:97]
	v_cvt_pk_bf16_f32 v106, v211, v212
	v_cvt_pk_bf16_f32 v107, v213, v214
	v_cvt_pk_bf16_f32 v108, v215, v216
	v_cvt_pk_bf16_f32 v109, v217, v218
	v_mfma_f32_32x32x16_bf16 v[66:81], v[118:121], v[134:137], v[66:81]
	v_mfma_f32_32x32x16_bf16 v[82:97], v[122:125], v[130:133], v[82:97]
	v_cvt_pk_bf16_f32 v98, v219, v220
	v_cvt_pk_bf16_f32 v99, v221, v222
	v_cvt_pk_bf16_f32 v100, v223, v234
	v_cvt_pk_bf16_f32 v101, v235, v236
	ds_read_b64_tr_b16 v[126:127], v237 offset:0
	ds_read_b64_tr_b16 v[128:129], v237 offset:0x400
	ds_read_b64_tr_b16 v[122:123], v237 offset:0x200
	v_mfma_f32_32x32x16_bf16 v[66:81], v[246:249], v[130:133], v[66:81]
	ds_read_b64_tr_b16 v[124:125], v237 offset:0x600
	ds_read_b64_tr_b16 v[118:119], v237 offset:0x800
	ds_read_b64_tr_b16 v[120:121], v237 offset:0xc00
	ds_read_b64_tr_b16 v[110:111], v237 offset:0xa00
	ds_read_b64_tr_b16 v[112:113], v237 offset:0xe00
	s_waitcnt lgkmcnt(0)
	ds_read_b64_tr_b16 v[228:229], v237 offset:0x1000
	ds_read_b64_tr_b16 v[230:231], v237 offset:0x1400
	ds_read_b64_tr_b16 v[238:239], v237 offset:0x1200
	ds_read_b64_tr_b16 v[240:241], v237 offset:0x1600
	ds_read_b64_tr_b16 v[242:243], v237 offset:0x1800
	ds_read_b64_tr_b16 v[244:245], v237 offset:0x1c00
	ds_read_b64_tr_b16 v[246:247], v237 offset:0x1a00
	ds_read_b64_tr_b16 v[248:249], v237 offset:0x1e00
	v_mfma_f32_32x32x16_bf16 v[18:33], v[114:117], v[126:129], v[18:33]
	v_add_f32_e32 v34, v195, v197
	v_add_f32_e32 v35, v198, v201
	v_add_f32_e32 v36, v196, v199
	v_add_f32_e32 v37, v200, v202
	v_add_f32_e32 v34, v34, v35
	v_add_f32_e32 v36, v36, v37
	v_mfma_f32_32x32x16_bf16 v[2:17], v[114:117], v[122:125], v[2:17]
	v_max_f32_e32 v114, v82, v83
	v_max3_f32 v115, v84, v85, v67
	v_max3_f32 v114, v114, v66, v68
	v_max3_f32 v115, v115, v86, v87
	v_mfma_f32_32x32x16_bf16 v[18:33], v[102:105], v[118:121], v[18:33]
	v_max3_f32 v114, v114, v69, v88
	v_max3_f32 v115, v115, v70, v71
	v_add_f32_e32 v34, v36, v34
	v_add_f32_e32 v35, v203, v204
	v_add_f32_e32 v37, v205, v206
	v_mfma_f32_32x32x16_bf16 v[2:17], v[102:105], v[110:113], v[2:17]
	v_max3_f32 v102, v114, v89, v72
	v_max3_f32 v103, v115, v90, v91
	v_max3_f32 v102, v102, v73, v92
	v_add_f32_e32 v35, v35, v37
	v_add_f32_e32 v36, v207, v208
	v_add_f32_e32 v37, v209, v210
	s_waitcnt lgkmcnt(0)
	v_mfma_f32_32x32x16_bf16 v[18:33], v[106:109], v[228:231], v[18:33]
	v_max3_f32 v103, v103, v74, v75
	v_max3_f32 v102, v102, v93, v76
	v_add_f32_e32 v34, v35, v34
	v_add_f32_e32 v36, v36, v37
	s_cmp_ge_u32 s39, s38
	s_cbranch_scc0 .Lmy_h1w
	s_waitcnt vmcnt(0)
